# scan: only the loader waves raised (priority 3), compute waves left at 0
# speedup vs baseline: 1.0142x; 1.0001x over previous
; #define GAS __attribute__((address_space(1)))
; #define MFMA16(a, b, c) __builtin_amdgcn_mfma_f32_16x16x32_f16((a), (b), (c), 0, 0, 0)
; #define LD_T(F, base_) do { _Pragma("unroll") for (int ti = 0; ti < 4; ++ti) _Pragma("unroll") for (int k2 = 0; k2 < 2; ++k2) { const h16* tp = (base_) + (16 * ti + fr) * 72 + 32 * k2 + 4 * g; \
;                     F[2 * ti + k2] = cat8(*(const h16x4*)tp, *(const h16x4*)(tp + 16)); } } while (0)
; __device__ __forceinline__ void phase_scan(h16* Pdn, const h16* Tg, const h16* qkg, const float* gcg, const float* betag, const float* s2g, unsigned char* ldsb) {
;     ...
;         for (int n = 0; n < 64; ++n) {
;             const unsigned tok0 = (unsigned)b * SEQ + 64 * n;
;             const h16* B = (const h16*)ldsb + (n & 1) * BUFH;
;             const h16* qn = B + OQ; const h16* kn = B + OK_; const h16* Tm = B + OT; const h16* qkm = B + OQK; const h16* vbs = B + OV;
;             const float* gcs = (const float*)(B + OSC); const float* bts = gcs + 64; const float* s2s = gcs + 128;
;             {
;                 GAS h16* ob = (GAS h16*)(Pdn + (tok0 * 4096 + 2048 + h * 128 + 64 * s));
;                 const float e_last = gcs[63];
;                 h16x8 Sf[4];
; #pragma unroll
;                 for (int kk = 0; kk < 4; ++kk)
; #pragma unroll
;                     for (int rg = 0; rg < 4; ++rg) { Sf[kk][rg] = (h16)S[2 * kk][rg]; Sf[kk][4 + rg] = (h16)S[2 * kk + 1][rg]; }
;     ...
;                 h16x8 F0[8], F1[8];
;                 f32x4 gc0, bt0, gc1 = {0.f, 0.f, 0.f, 0.f}, bt1 = {0.f, 0.f, 0.f, 0.f}; h16x4 vb0, vb1 = {0, 0, 0, 0};
;                 LD_A(F0, 0); LD_S(gc0, bt0, vb0, 0);
;                 f32x4 R[4], O[4];
; #pragma unroll
;                 for (int ti = 0; ti < 4; ++ti) {
;                     if (ti < 3) { LD_A(F1, ti + 1); LD_S(gc1, bt1, vb1, ti + 1); } else LD_T(F1, Tm);
;                     __builtin_amdgcn_sched_barrier(0);
;                     f32x4 ka = {0.f, 0.f, 0.f, 0.f}, qa = {0.f, 0.f, 0.f, 0.f};
; #pragma unroll
;                     for (int kk = 0; kk < 4; ++kk) { ka = MFMA16(F0[2 * kk], Sf[kk], ka); qa = MFMA16(F0[2 * kk + 1], Sf[kk], qa); }
; #pragma unroll
;                     for (int rg = 0; rg < 4; ++rg) { R[ti][rg] = (float)vb0[rg] - bt0[rg] * ka[rg]; O[ti][rg] = gc0[rg] * qa[rg]; }
;                     CP_F(F0, F1); gc0 = gc1; bt0 = bt1; vb0 = vb1;
;                 }
.LBB0_247:
	s_bitcmp1_b32 s7, 0
	s_cselect_b32 s0, 0xf300, 0
	s_add_i32 s9, s0, 0
	s_lshl_b64 s[0:1], s[12:13], 1
	s_add_u32 s0, s86, s0
	v_lshl_add_u32 v179, v171, 1, s9
	s_addc_u32 s1, s87, s1
	v_add_u32_e32 v70, v179, v177
	s_lshl_b32 s10, s6, 1
	v_add_u32_e32 v50, 0x4000, v70
	s_add_i32 s10, s9, s10
	v_mov_b32_e32 v32, s9
	ds_read2_b64 v[34:37], v50 offset0:128 offset1:132
	ds_read2_b64 v[38:41], v70 offset1:4
	ds_read2_b64 v[42:45], v50 offset0:136 offset1:140
	ds_read2_b64 v[58:61], v70 offset0:8 offset1:12
	ds_read2_b64 v[74:77], v50 offset0:144 offset1:148
	ds_read2_b64 v[78:81], v70 offset0:16 offset1:20
	ds_read2_b64 v[82:85], v50 offset0:152 offset1:156
	ds_read2_b64 v[86:89], v70 offset0:24 offset1:28
	v_lshl_add_u32 v136, v171, 2, s9
	v_add3_u32 v50, s10, v172, v178
	v_add3_u32 v137, s10, v178, v172
	v_add_u32_e32 v71, 0x1000, v70
	v_add_u32_e32 v70, 0x5000, v70
	ds_read_b32 v32, v32 offset:61692
	ds_read_b128 v[90:93], v136 offset:61440
	ds_read_b128 v[54:57], v136 offset:61696
	ds_read_b128 v[94:97], v136 offset:61504
	ds_read_b64_tr_b16 v[108:109], v50 offset:53248
	ds_read_b128 v[50:53], v136 offset:61760
	ds_read_b64_tr_b16 v[106:107], v137 offset:55296
	ds_read2_b64 v[98:101], v71 offset0:56 offset1:60
	ds_read2_b64 v[102:105], v70 offset0:184 offset1:188
	ds_read2_b64 v[110:113], v71 offset0:48 offset1:52
	ds_read2_b64 v[116:119], v70 offset0:176 offset1:180
	ds_read2_b64 v[120:123], v71 offset0:40 offset1:44
	ds_read2_b64 v[124:127], v70 offset0:168 offset1:172
	ds_read2_b64 v[128:131], v71 offset0:32 offset1:36
	ds_read2_b64 v[132:135], v70 offset0:160 offset1:164
	v_cvt_pk_f16_f32 v49, v10, v11
	v_cvt_pk_f16_f32 v48, v8, v9
	v_cvt_pk_f16_f32 v47, v14, v15
	v_cvt_pk_f16_f32 v46, v12, v13
	v_cvt_pk_f16_f32 v65, v2, v3
	v_cvt_pk_f16_f32 v64, v0, v1
	v_cvt_pk_f16_f32 v63, v6, v7
	v_cvt_pk_f16_f32 v62, v4, v5
	v_cvt_pk_f16_f32 v69, v22, v23
	v_cvt_pk_f16_f32 v68, v20, v21
	v_cvt_pk_f16_f32 v67, v18, v19
	v_cvt_pk_f16_f32 v66, v16, v17
	v_cvt_pk_f16_f32 v73, v30, v31
	v_cvt_pk_f16_f32 v72, v28, v29
	v_cvt_pk_f16_f32 v71, v26, v27
	v_cvt_pk_f16_f32 v70, v24, v25
	v_add_u32_e32 v180, v136, v176
	s_waitcnt lgkmcnt(0)
	v_mfma_f32_16x16x32_f16 v[34:37], v[34:37], v[46:49], 0
	v_add_u32_e32 v181, v180, v177
	v_mfma_f32_16x16x32_f16 v[38:41], v[38:41], v[46:49], 0
	v_mfma_f32_16x16x32_f16 v[34:37], v[42:45], v[62:65], v[34:37]
	v_mfma_f32_16x16x32_f16 v[38:41], v[58:61], v[62:65], v[38:41]
	ds_read_b128 v[42:45], v136 offset:61568
	ds_read_b128 v[58:61], v136 offset:61824
	ds_read_b64_tr_b16 v[114:115], v137 offset:57344
	v_mfma_f32_16x16x32_f16 v[34:37], v[74:77], v[66:69], v[34:37]
	v_mfma_f32_16x16x32_f16 v[38:41], v[78:81], v[66:69], v[38:41]
	v_mfma_f32_16x16x32_f16 v[74:77], v[82:85], v[70:73], v[34:37]
	v_mfma_f32_16x16x32_f16 v[34:37], v[86:89], v[70:73], v[38:41]
	s_nop 5
	v_add_u32_e32 v38, 0x2000, v181
	v_add_u32_e32 v39, 0x6000, v181
	v_pk_mul_f32 v[36:37], v[92:93], v[36:37]
	v_pk_mul_f32 v[34:35], v[90:91], v[34:35]
	ds_read2_b64 v[90:93], v38 offset0:88 offset1:92
	ds_read2_b64 v[86:89], v39 offset0:216 offset1:220
	ds_read2_b64 v[204:207], v38 offset0:80 offset1:84
	ds_read2_b64 v[208:211], v39 offset0:208 offset1:212
	ds_read2_b64 v[212:215], v38 offset0:72 offset1:76
	ds_read2_b64 v[216:219], v39 offset0:200 offset1:204
	ds_read2_b64 v[220:223], v38 offset0:64 offset1:68
	ds_read2_b64 v[224:227], v39 offset0:192 offset1:196
	v_mfma_f32_16x16x32_f16 v[38:41], v[132:135], v[46:49], 0
	v_mfma_f32_16x16x32_f16 v[78:81], v[128:131], v[46:49], 0
	v_mfma_f32_16x16x32_f16 v[38:41], v[124:127], v[62:65], v[38:41]
	v_mfma_f32_16x16x32_f16 v[78:81], v[120:123], v[62:65], v[78:81]
	v_mfma_f32_16x16x32_f16 v[38:41], v[116:119], v[66:69], v[38:41]
	v_mfma_f32_16x16x32_f16 v[78:81], v[110:113], v[66:69], v[78:81]
	v_mfma_f32_16x16x32_f16 v[82:85], v[102:105], v[70:73], v[38:41]
	v_mfma_f32_16x16x32_f16 v[38:41], v[98:101], v[70:73], v[78:81]
	ds_read_b128 v[118:121], v136 offset:61632
	s_nop 4
	ds_read_b128 v[78:81], v136 offset:61888
	ds_read_b64_tr_b16 v[116:117], v137 offset:59392
	v_pk_mul_f32 v[38:39], v[94:95], v[38:39]
	v_add_u32_e32 v94, 0x3000, v181
	v_add_u32_e32 v95, 0x7000, v181
	ds_read2_b64 v[122:125], v94 offset0:120 offset1:124
	ds_read2_b64 v[228:231], v95 offset0:248 offset1:252
	ds_read2_b64 v[232:235], v94 offset0:112 offset1:116
	ds_read2_b64 v[236:239], v95 offset0:240 offset1:244
	ds_read2_b64 v[240:243], v94 offset0:104 offset1:108
	ds_read2_b64 v[244:247], v95 offset0:232 offset1:236
	ds_read2_b64 v[248:251], v94 offset0:96 offset1:100
	ds_read2_b64 v[196:199], v95 offset0:224 offset1:228
	v_pk_mul_f32 v[40:41], v[96:97], v[40:41]
	s_waitcnt lgkmcnt(12)
	v_mfma_f32_16x16x32_f16 v[98:101], v[220:223], v[46:49], 0
	v_add_u32_e32 v130, v180, v173
	v_add_u32_e32 v102, 0x9800, v130
	v_add_u32_e32 v126, 0x9000, v130
	s_waitcnt lgkmcnt(11)
	v_mfma_f32_16x16x32_f16 v[94:97], v[224:227], v[46:49], 0
	v_add_u32_e32 v134, 0x8800, v130
	v_mfma_f32_16x16x32_f16 v[98:101], v[212:215], v[62:65], v[98:101]
	v_mfma_f32_16x16x32_f16 v[94:97], v[216:219], v[62:65], v[94:97]
	v_mfma_f32_16x16x32_f16 v[98:101], v[204:207], v[66:69], v[98:101]
	v_mfma_f32_16x16x32_f16 v[94:97], v[208:211], v[66:69], v[94:97]
	v_mfma_f32_16x16x32_f16 v[90:93], v[90:93], v[70:73], v[98:101]
	v_mfma_f32_16x16x32_f16 v[86:89], v[86:89], v[70:73], v[94:97]
	s_nop 5
	v_add_u32_e32 v94, 0xa000, v130
	v_pk_mul_f32 v[44:45], v[44:45], v[92:93]
	v_pk_mul_f32 v[42:43], v[42:43], v[90:91]
	ds_read2_b64 v[90:93], v94 offset0:104 offset1:108
	ds_read2_b64 v[94:97], v94 offset0:96 offset1:100
	ds_read2_b64 v[98:101], v102 offset0:72 offset1:76
	ds_read2_b64 v[102:105], v102 offset0:64 offset1:68
	ds_read2_b64 v[110:113], v126 offset0:40 offset1:44
	ds_read2_b64 v[126:129], v126 offset0:32 offset1:36
	ds_read2_b64 v[130:133], v134 offset0:8 offset1:12
	ds_read2_b64 v[134:137], v134 offset1:4
	s_waitcnt lgkmcnt(8)
; #define MFMA16(a, b, c) __builtin_amdgcn_mfma_f32_16x16x32_f16((a), (b), (c), 0, 0, 0)
; #define LD_T(F, base_) do { _Pragma("unroll") for (int ti = 0; ti < 4; ++ti) _Pragma("unroll") for (int k2 = 0; k2 < 2; ++k2) { const h16* tp = (base_) + (16 * ti + fr) * 72 + 32 * k2 + 4 * g; \
;                     F[2 * ti + k2] = cat8(*(const h16x4*)tp, *(const h16x4*)(tp + 16)); } } while (0)
; #define CP_F(D, S_) do { _Pragma("unroll") for (int q = 0; q < 8; ++q) D[q] = S_[q]; } while (0)
; __device__ __forceinline__ void phase_scan(h16* Pdn, const h16* Tg, const h16* qkg, const float* gcg, const float* betag, const float* s2g, unsigned char* ldsb) {
;     ...
;                     for (int rg = 0; rg < 4; ++rg) { R[ti][rg] = (float)vb0[rg] - bt0[rg] * ka[rg]; O[ti][rg] = gc0[rg] * qa[rg]; }
;                     CP_F(F0, F1); gc0 = gc1; bt0 = bt1; vb0 = vb1;
;                 }
;                 h16x8 Rf[2];
; #pragma unroll
;                 for (int k2 = 0; k2 < 2; ++k2)
; #pragma unroll
;                     for (int rg = 0; rg < 4; ++rg) { Rf[k2][rg] = (h16)R[2 * k2][rg]; Rf[k2][4 + rg] = (h16)R[2 * k2 + 1][rg]; }
;                 LD_T(F1, qkm);
;                 __builtin_amdgcn_sched_barrier(0);
;                 f32x4 Vn[4];
; #pragma unroll
;                 for (int ti = 0; ti < 4; ++ti) {
;                     f32x4 acc = {0.f, 0.f, 0.f, 0.f};
; #pragma unroll
;                     for (int k2 = 0; k2 < 2; ++k2) acc = MFMA16(F0[2 * ti + k2], Rf[k2], acc);
;                     Vn[ti] = acc;
;                 }
;                 CP_F(F0, F1);
;                 h16x8 Vf[2], V2f[2];
; #pragma unroll
;                 for (int k2 = 0; k2 < 2; ++k2) {
;                     const f32x4 gca = *(const f32x4*)(s2s + 32 * k2 + 4 * g), gcb = *(const f32x4*)(s2s + 32 * k2 + 16 + 4 * g);
; #pragma unroll
;                     for (int rg = 0; rg < 4; ++rg) {
;                         Vf[k2][rg] = (h16)Vn[2 * k2][rg]; Vf[k2][4 + rg] = (h16)Vn[2 * k2 + 1][rg];
;                         V2f[k2][rg] = (h16)(Vn[2 * k2][rg] * gca[rg]); V2f[k2][4 + rg] = (h16)(Vn[2 * k2 + 1][rg] * gcb[rg]);
;                     }
;                 }
	v_mfma_f32_16x16x32_f16 v[196:199], v[196:199], v[46:49], 0
	v_mfma_f32_16x16x32_f16 v[46:49], v[248:251], v[46:49], 0
	v_mfma_f32_16x16x32_f16 v[196:199], v[244:247], v[62:65], v[196:199]
	v_mfma_f32_16x16x32_f16 v[46:49], v[240:243], v[62:65], v[46:49]
	v_mfma_f32_16x16x32_f16 v[62:65], v[236:239], v[66:69], v[196:199]
	v_mfma_f32_16x16x32_f16 v[46:49], v[232:235], v[66:69], v[46:49]
	v_cvt_f32_f16_e32 v66, v108
	v_cvt_f32_f16_sdwa v67, v108 dst_sel:DWORD dst_unused:UNUSED_PAD src0_sel:WORD_1
	v_pk_fma_f32 v[54:55], v[54:55], v[74:75], v[66:67] neg_lo:[1,0,0] neg_hi:[1,0,0]
	s_nop 0
	v_cvt_pk_f16_f32 v66, v54, v55
	v_cvt_f32_f16_e32 v54, v106
	v_cvt_f32_f16_sdwa v55, v106 dst_sel:DWORD dst_unused:UNUSED_PAD src0_sel:WORD_1
	v_mfma_f32_16x16x32_f16 v[62:65], v[228:231], v[70:73], v[62:65]
	v_fma_f32 v50, -v50, v82, v54
	v_fma_f32 v51, -v51, v83, v55
	v_cvt_pk_f16_f32 v68, v50, v51
	v_cvt_f32_f16_e32 v50, v109
	v_cvt_f32_f16_sdwa v51, v109 dst_sel:DWORD dst_unused:UNUSED_PAD src0_sel:WORD_1
	v_cvt_f32_f16_e32 v54, v115
	v_cvt_f32_f16_sdwa v55, v115 dst_sel:DWORD dst_unused:UNUSED_PAD src0_sel:WORD_1
	v_mfma_f32_16x16x32_f16 v[46:49], v[122:125], v[70:73], v[46:49]
	v_fma_f32 v50, -v56, v76, v50
	v_fma_f32 v51, -v57, v77, v51
	v_pk_fma_f32 v[54:55], v[60:61], v[88:89], v[54:55] neg_lo:[1,0,0] neg_hi:[1,0,0]
	v_cvt_pk_f16_f32 v67, v50, v51
	v_cvt_f32_f16_e32 v50, v107
	v_cvt_f32_f16_sdwa v51, v107 dst_sel:DWORD dst_unused:UNUSED_PAD src0_sel:WORD_1
	s_nop 1
	v_pk_mul_f32 v[48:49], v[120:121], v[48:49]
	v_pk_mul_f32 v[46:47], v[118:119], v[46:47]
	v_pk_fma_f32 v[50:51], v[52:53], v[84:85], v[50:51] neg_lo:[1,0,0] neg_hi:[1,0,0]
	s_nop 0
	v_cvt_pk_f16_f32 v69, v50, v51
	v_cvt_f32_f16_e32 v50, v114
	v_cvt_f32_f16_sdwa v51, v114 dst_sel:DWORD dst_unused:UNUSED_PAD src0_sel:WORD_1
	v_cvt_f32_f16_e32 v52, v116
	v_cvt_f32_f16_sdwa v53, v116 dst_sel:DWORD dst_unused:UNUSED_PAD src0_sel:WORD_1
	v_pk_fma_f32 v[50:51], v[58:59], v[86:87], v[50:51] neg_lo:[1,0,0] neg_hi:[1,0,0]
	s_nop 0
	v_cvt_pk_f16_f32 v50, v50, v51
	v_cvt_pk_f16_f32 v51, v54, v55
	v_cvt_f32_f16_e32 v54, v117
	v_cvt_f32_f16_sdwa v55, v117 dst_sel:DWORD dst_unused:UNUSED_PAD src0_sel:WORD_1
	v_pk_fma_f32 v[52:53], v[78:79], v[62:63], v[52:53] neg_lo:[1,0,0] neg_hi:[1,0,0]
	v_pk_fma_f32 v[54:55], v[80:81], v[64:65], v[54:55] neg_lo:[1,0,0] neg_hi:[1,0,0]
	v_cvt_pk_f16_f32 v52, v52, v53
	v_cvt_pk_f16_f32 v53, v54, v55
	v_add_u32_e32 v54, v179, v173
	v_add_u32_e32 v55, 0xa800, v54
	ds_read2_b64 v[118:121], v55 offset0:128 offset1:132
	ds_read2_b64 v[122:125], v55 offset0:136 offset1:140
	v_add_u32_e32 v55, 0xb000, v54
	ds_read2_b64 v[114:117], v55 offset0:160 offset1:164
	ds_read2_b64 v[106:109], v55 offset0:168 offset1:172
	v_add_u32_e32 v55, 0xb800, v54
	v_add_u32_e32 v54, 0xc000, v54
	ds_read2_b64 v[86:89], v55 offset0:192 offset1:196
	ds_read2_b64 v[82:85], v55 offset0:200 offset1:204
	ds_read2_b64 v[62:65], v54 offset0:224 offset1:228
	ds_read2_b64 v[58:61], v54 offset0:232 offset1:236
	s_waitcnt lgkmcnt(8)
	v_mfma_f32_16x16x32_f16 v[54:57], v[134:137], v[66:69], 0
	v_mfma_f32_16x16x32_f16 v[70:73], v[126:129], v[66:69], 0
	v_mfma_f32_16x16x32_f16 v[74:77], v[102:105], v[66:69], 0
	v_add3_u32 v104, s9, v178, v174
	v_mfma_f32_16x16x32_f16 v[66:69], v[94:97], v[66:69], 0
	v_mfma_f32_16x16x32_f16 v[66:69], v[90:93], v[50:53], v[66:69]
	v_add_u32_e32 v92, v179, v175
	v_mfma_f32_16x16x32_f16 v[54:57], v[130:133], v[50:53], v[54:57]
	v_mfma_f32_16x16x32_f16 v[70:73], v[110:113], v[50:53], v[70:73]
	s_nop 4
	v_cvt_pk_f16_f32 v128, v66, v67
	s_nop 0
	v_cvt_pk_f16_f32 v110, v54, v55
	v_cvt_pk_f16_f32 v111, v56, v57
	v_mfma_f32_16x16x32_f16 v[74:77], v[98:101], v[50:53], v[74:77]
	ds_read_b128 v[50:53], v92 offset:61952
	ds_read_b128 v[78:81], v92 offset:62016
	v_cvt_pk_f16_f32 v113, v72, v73
	v_cvt_pk_f16_f32 v112, v70, v71
	v_cvt_pk_f16_f32 v129, v68, v69
	s_waitcnt lgkmcnt(1)
	v_pk_mul_f32 v[90:91], v[56:57], v[52:53]
	v_mul_f32_e32 v51, v55, v51
	v_fma_mixlo_f16 v93, v54, v50, 0
	v_pk_mov_b32 v[50:51], v[50:51], v[90:91] op_sel:[1,0]
	s_waitcnt lgkmcnt(0)
	v_pk_mul_f32 v[90:91], v[70:71], v[78:79]
	v_mul_f32_e32 v80, v72, v80
	v_pk_mov_b32 v[90:91], v[90:91], v[80:81] op_sel:[1,0]
	v_pk_mov_b32 v[54:55], v[56:57], v[70:71] op_sel:[1,0]
	v_pk_mov_b32 v[52:53], v[52:53], v[78:79] op_sel:[1,0]
	v_cvt_pk_f16_f32 v80, v90, v91
	v_pk_mul_f32 v[52:53], v[54:55], v[52:53]
	v_cvt_pk_f16_f32 v51, v50, v51
	v_cvt_pk_f16_f32 v52, v52, v53
	v_lshrrev_b32_e32 v53, 16, v80
	v_fma_mixhi_f16 v53, v73, v81, 0
	ds_read_b128 v[54:57], v92 offset:62080
	ds_read_b128 v[70:73], v92 offset:62144
	v_pack_b32_f16 v50, v93, v51
	v_alignbit_b32 v51, v52, v51, 16
	v_alignbit_b32 v52, v80, v52, 16
	s_waitcnt lgkmcnt(1)
	v_pk_mul_f32 v[78:79], v[76:77], v[56:57]
	v_mul_f32_e32 v55, v75, v55
	v_fma_mixlo_f16 v80, v74, v54, 0
	v_pk_mov_b32 v[54:55], v[54:55], v[78:79] op_sel:[1,0]
	s_waitcnt lgkmcnt(0)
; #define LDS_BARRIER() do { asm volatile("s_waitcnt lgkmcnt(0)" ::: "memory"); __builtin_amdgcn_s_barrier(); asm volatile("" ::: "memory"); } while (0)
; #define MFMA16(a, b, c) __builtin_amdgcn_mfma_f32_16x16x32_f16((a), (b), (c), 0, 0, 0)
; #define LD_K(F, tk0_) do { _Pragma("unroll") for (int t = 0; t < 4; ++t) _Pragma("unroll") for (int k2 = 0; k2 < 2; ++k2) { const h16* kp = kn + (32 * k2 + 4 * g + (fr >> 2)) * 136 + 16 * ((tk0_) + t) + 4 * (fr & 3); \
;                     F[2 * t + k2] = cat8(tr_read4(kp), tr_read4(kp + 16 * 136)); } } while (0)
; #define CP_F(D, S_) do { _Pragma("unroll") for (int q = 0; q < 8; ++q) D[q] = S_[q]; } while (0)
; __device__ __forceinline__ void phase_scan(h16* Pdn, const h16* Tg, const h16* qkg, const float* gcg, const float* betag, const float* s2g, unsigned char* ldsb) {
;     ...
;                 LD_K(F1, 0);
;                 __builtin_amdgcn_sched_barrier(0);
; #pragma unroll
;                 for (int ti = 0; ti < 4; ++ti) {
; #pragma unroll
;                     for (int k2 = 0; k2 < 2; ++k2) O[ti] = MFMA16(F0[2 * ti + k2], Vf[k2], O[ti]);
; #pragma unroll
;                     for (int rg = 0; rg < 4; ++rg) {
;                         const int i = 16 * ti + 4 * g + rg;
;                         ob[i * 4096 + 16 * w + fr] = (h16)O[ti][rg];
;                     }
;                 }
;                 CP_F(F0, F1);
;                 LD_K(F1, 4);
;                 __builtin_amdgcn_sched_barrier(0);
; #pragma unroll
;                 for (int t = 0; t < 4; ++t) {
;                     f32x4 acc = S[t] * e_last;
; #pragma unroll
;                     for (int k2 = 0; k2 < 2; ++k2) acc = MFMA16(F0[2 * t + k2], V2f[k2], acc);
;                     S[t] = acc;
;                 }
;                 __builtin_amdgcn_sched_barrier(0);
; #pragma unroll
;                 for (int t = 0; t < 4; ++t) {
;                     f32x4 acc = S[4 + t] * e_last;
; #pragma unroll
;                     for (int k2 = 0; k2 < 2; ++k2) acc = MFMA16(F1[2 * t + k2], V2f[k2], acc);
;                     S[4 + t] = acc;
;                 }
;     ...
;             }
;             LDS_BARRIER();
	v_pk_mul_f32 v[78:79], v[66:67], v[70:71]
	v_mul_f32_e32 v72, v68, v72
	v_pk_mov_b32 v[78:79], v[78:79], v[72:73] op_sel:[1,0]
	v_pk_mov_b32 v[66:67], v[76:77], v[66:67] op_sel:[1,0]
	v_pk_mov_b32 v[56:57], v[56:57], v[70:71] op_sel:[1,0]
	v_cvt_pk_f16_f32 v72, v78, v79
	v_pk_mul_f32 v[56:57], v[66:67], v[56:57]
	v_cvt_pk_f16_f32 v55, v54, v55
	v_cvt_pk_f16_f32 v56, v56, v57
	v_lshrrev_b32_e32 v57, 16, v72
	v_pack_b32_f16 v54, v80, v55
	v_cvt_pk_f16_f32 v127, v76, v77
	v_cvt_pk_f16_f32 v126, v74, v75
	v_alignbit_b32 v55, v56, v55, 16
	v_alignbit_b32 v56, v72, v56, 16
	v_fma_mixhi_f16 v57, v69, v73, 0
	ds_read_b64_tr_b16 v[76:77], v104 offset:21760
	ds_read_b64_tr_b16 v[74:75], v104 offset:17408
	ds_read_b64_tr_b16 v[66:67], v104 offset:17440
	ds_read_b64_tr_b16 v[78:79], v104 offset:26112
	ds_read_b64_tr_b16 v[80:81], v104 offset:30464
	ds_read_b64_tr_b16 v[68:69], v104 offset:21792
	ds_read_b64_tr_b16 v[70:71], v104 offset:26144
	ds_read_b64_tr_b16 v[72:73], v104 offset:30496
	ds_read_b64_tr_b16 v[90:91], v104 offset:17472
	ds_read_b64_tr_b16 v[92:93], v104 offset:21824
	ds_read_b64_tr_b16 v[94:95], v104 offset:26176
	ds_read_b64_tr_b16 v[96:97], v104 offset:30528
	ds_read_b64_tr_b16 v[98:99], v104 offset:17504
	ds_read_b64_tr_b16 v[100:101], v104 offset:21856
	ds_read_b64_tr_b16 v[102:103], v104 offset:26208
	ds_read_b64_tr_b16 v[104:105], v104 offset:30560
	v_mfma_f32_16x16x32_f16 v[34:37], v[118:121], v[110:113], v[34:37]
	v_lshl_add_u64 v[118:119], v[138:139], 1, s[0:1]
	v_mfma_f32_16x16x32_f16 v[34:37], v[122:125], v[126:129], v[34:37]
	s_nop 7
	v_cvt_f16_f32_e32 v34, v34
	v_cvt_f16_f32_e32 v36, v36
	global_store_short v[118:119], v34, off
	v_cvt_f16_f32_e32 v118, v35
	v_lshl_add_u64 v[34:35], v[140:141], 1, s[0:1]
	global_store_short v[34:35], v118, off
	v_lshl_add_u64 v[34:35], v[142:143], 1, s[0:1]
	global_store_short v[34:35], v36, off
	v_cvt_f16_f32_e32 v36, v37
	v_lshl_add_u64 v[34:35], v[144:145], 1, s[0:1]
	global_store_short v[34:35], v36, off
	v_mfma_f32_16x16x32_f16 v[34:37], v[114:117], v[110:113], v[38:41]
	v_mfma_f32_16x16x32_f16 v[34:37], v[106:109], v[126:129], v[34:37]
	s_nop 1
	v_lshl_add_u64 v[38:39], v[146:147], 1, s[0:1]
	s_nop 4
	v_cvt_f16_f32_e32 v34, v34
	v_cvt_f16_f32_e32 v36, v36
	global_store_short v[38:39], v34, off
	v_cvt_f16_f32_e32 v38, v35
	v_lshl_add_u64 v[34:35], v[148:149], 1, s[0:1]
	global_store_short v[34:35], v38, off
	v_lshl_add_u64 v[34:35], v[150:151], 1, s[0:1]
	global_store_short v[34:35], v36, off
	v_cvt_f16_f32_e32 v36, v37
	v_lshl_add_u64 v[34:35], v[152:153], 1, s[0:1]
	v_lshl_add_u64 v[38:39], v[154:155], 1, s[0:1]
	global_store_short v[34:35], v36, off
	v_mfma_f32_16x16x32_f16 v[34:37], v[86:89], v[110:113], v[42:45]
	v_add3_u32 v88, s9, v174, v178
	v_mfma_f32_16x16x32_f16 v[34:37], v[82:85], v[126:129], v[34:37]
	s_nop 7
	v_cvt_f16_f32_e32 v34, v34
	v_cvt_f16_f32_e32 v36, v36
	global_store_short v[38:39], v34, off
	v_cvt_f16_f32_e32 v38, v35
	v_lshl_add_u64 v[34:35], v[156:157], 1, s[0:1]
	global_store_short v[34:35], v38, off
	v_lshl_add_u64 v[34:35], v[158:159], 1, s[0:1]
	global_store_short v[34:35], v36, off
	v_cvt_f16_f32_e32 v36, v37
	v_lshl_add_u64 v[34:35], v[160:161], 1, s[0:1]
	v_lshl_add_u64 v[38:39], v[162:163], 1, s[0:1]
	global_store_short v[34:35], v36, off
	v_mfma_f32_16x16x32_f16 v[34:37], v[62:65], v[110:113], v[46:49]
	v_mfma_f32_16x16x32_f16 v[34:37], v[58:61], v[126:129], v[34:37]
	s_nop 7
	v_cvt_f16_f32_e32 v34, v34
	v_cvt_f16_f32_e32 v36, v36
	global_store_short v[38:39], v34, off
	v_cvt_f16_f32_e32 v38, v35
	v_lshl_add_u64 v[34:35], v[164:165], 1, s[0:1]
	global_store_short v[34:35], v38, off
	v_lshl_add_u64 v[34:35], v[166:167], 1, s[0:1]
	global_store_short v[34:35], v36, off
	v_cvt_f16_f32_e32 v36, v37
	v_lshl_add_u64 v[34:35], v[168:169], 1, s[0:1]
	global_store_short v[34:35], v36, off
	ds_read_b64_tr_b16 v[36:37], v88 offset:21888
	ds_read_b64_tr_b16 v[34:35], v88 offset:17536
	ds_read_b64_tr_b16 v[38:39], v88 offset:17568
	ds_read_b64_tr_b16 v[42:43], v88 offset:26240
	ds_read_b64_tr_b16 v[44:45], v88 offset:30592
	ds_read_b64_tr_b16 v[40:41], v88 offset:21920
	ds_read_b64_tr_b16 v[46:47], v88 offset:26272
	ds_read_b64_tr_b16 v[48:49], v88 offset:30624
	ds_read_b64_tr_b16 v[58:59], v88 offset:17600
	ds_read_b64_tr_b16 v[60:61], v88 offset:21952
	ds_read_b64_tr_b16 v[62:63], v88 offset:26304
	ds_read_b64_tr_b16 v[64:65], v88 offset:30656
	ds_read_b64_tr_b16 v[82:83], v88 offset:17632
	ds_read_b64_tr_b16 v[84:85], v88 offset:21984
	ds_read_b64_tr_b16 v[86:87], v88 offset:26336
	ds_read_b64_tr_b16 v[88:89], v88 offset:30688
	v_pk_mul_f32 v[14:15], v[14:15], v[32:33] op_sel_hi:[1,0]
	v_pk_mul_f32 v[12:13], v[12:13], v[32:33] op_sel_hi:[1,0]
	v_pk_mul_f32 v[10:11], v[10:11], v[32:33] op_sel_hi:[1,0]
	v_pk_mul_f32 v[8:9], v[8:9], v[32:33] op_sel_hi:[1,0]
	v_pk_mul_f32 v[6:7], v[6:7], v[32:33] op_sel_hi:[1,0]
	v_pk_mul_f32 v[4:5], v[4:5], v[32:33] op_sel_hi:[1,0]
	v_pk_mul_f32 v[2:3], v[2:3], v[32:33] op_sel_hi:[1,0]
	v_pk_mul_f32 v[0:1], v[0:1], v[32:33] op_sel_hi:[1,0]
	s_waitcnt lgkmcnt(14)
	v_mfma_f32_16x16x32_f16 v[12:15], v[74:77], v[50:53], v[12:15]
	v_mfma_f32_16x16x32_f16 v[8:11], v[66:69], v[50:53], v[8:11]
	v_mfma_f32_16x16x32_f16 v[4:7], v[90:93], v[50:53], v[4:7]
	v_mfma_f32_16x16x32_f16 v[0:3], v[98:101], v[50:53], v[0:3]
	v_mfma_f32_16x16x32_f16 v[12:15], v[78:81], v[54:57], v[12:15]
	v_mfma_f32_16x16x32_f16 v[8:11], v[70:73], v[54:57], v[8:11]
	v_mfma_f32_16x16x32_f16 v[4:7], v[94:97], v[54:57], v[4:7]
	v_mfma_f32_16x16x32_f16 v[0:3], v[102:105], v[54:57], v[0:3]
	v_mul_f32_e64 v18, v18, v32
	v_mul_f32_e64 v19, v19, v32
	v_pk_mul_f32 v[16:17], v[16:17], v[32:33] op_sel_hi:[1,0]
	v_pk_mul_f32 v[22:23], v[22:23], v[32:33] op_sel_hi:[1,0]
	v_pk_mul_f32 v[20:21], v[20:21], v[32:33] op_sel_hi:[1,0]
	v_pk_mul_f32 v[26:27], v[26:27], v[32:33] op_sel_hi:[1,0]
	v_pk_mul_f32 v[24:25], v[24:25], v[32:33] op_sel_hi:[1,0]
	v_pk_mul_f32 v[30:31], v[30:31], v[32:33] op_sel_hi:[1,0]
	v_pk_mul_f32 v[28:29], v[28:29], v[32:33] op_sel_hi:[1,0]
	v_mfma_f32_16x16x32_f16 v[16:19], v[34:37], v[50:53], v[16:19]
	s_waitcnt lgkmcnt(0)
	s_barrier
; #define LDS_BARRIER() do { asm volatile("s_waitcnt lgkmcnt(0)" ::: "memory"); __builtin_amdgcn_s_barrier(); asm volatile("" ::: "memory"); } while (0)
; #define MFMA16(a, b, c) __builtin_amdgcn_mfma_f32_16x16x32_f16((a), (b), (c), 0, 0, 0)
; __device__ __forceinline__ void phase_scan(h16* Pdn, const h16* Tg, const h16* qkg, const float* gcg, const float* betag, const float* s2g, unsigned char* ldsb) {
;     ...
;                 for (int t = 0; t < 4; ++t) {
;                     f32x4 acc = S[4 + t] * e_last;
; #pragma unroll
;                     for (int k2 = 0; k2 < 2; ++k2) acc = MFMA16(F1[2 * t + k2], V2f[k2], acc);
;                     S[4 + t] = acc;
;                 }
;     ...
;             }
;             LDS_BARRIER();
;         }
	s_waitcnt lgkmcnt(10)
	v_mfma_f32_16x16x32_f16 v[20:23], v[38:41], v[50:53], v[20:23]
	s_add_i32 s7, s7, 1
	s_add_i32 s12, s12, 0x40000
	s_cmp_eq_u32 s7, 64
	s_waitcnt lgkmcnt(6)
	v_mfma_f32_16x16x32_f16 v[24:27], v[58:61], v[50:53], v[24:27]
	s_waitcnt lgkmcnt(2)
	v_mfma_f32_16x16x32_f16 v[28:31], v[82:85], v[50:53], v[28:31]
	v_mfma_f32_16x16x32_f16 v[16:19], v[42:45], v[54:57], v[16:19]
	v_mfma_f32_16x16x32_f16 v[20:23], v[46:49], v[54:57], v[20:23]
	v_mfma_f32_16x16x32_f16 v[24:27], v[62:65], v[54:57], v[24:27]
	s_waitcnt lgkmcnt(0)
	v_mfma_f32_16x16x32_f16 v[28:31], v[86:89], v[54:57], v[28:31]
	s_cbranch_scc0 .LBB0_247
	v_writelane_b32 v254, s4, 43
	s_mov_b64 s[0:1], 0
	s_nop 0
	v_writelane_b32 v254, s5, 44
	v_writelane_b32 v254, s6, 45
	v_writelane_b32 v254, s7, 46
	v_writelane_b32 v254, s8, 47
	v_writelane_b32 v254, s9, 48
	v_writelane_b32 v254, s10, 49
	v_writelane_b32 v254, s11, 50
	v_writelane_b32 v254, s12, 51
	v_writelane_b32 v254, s13, 52
	v_writelane_b32 v254, s14, 53
	v_writelane_b32 v254, s15, 54
	v_writelane_b32 v254, s16, 55
	v_writelane_b32 v254, s17, 56
	v_writelane_b32 v254, s18, 57
	v_writelane_b32 v254, s19, 58
